# mix3 HGRN chunk loop: next chunk's global loads issued before the staging barrier instead of after it
# baseline (speedup 1.0000x reference)
.LBB0_1120:
	s_or_b64 exec, exec, s[16:17]
	v_and_b32_e32 v187, 0xffff0000, v91
	v_and_b32_e32 v188, 0xffff0000, v107
	v_mul_f32_e32 v175, v175, v187
	v_mul_f32_e32 v187, v183, v188
	v_mul_f32_e32 v183, 0x3fb8aa3b, v138
	v_mul_f32_e32 v186, 0x3fb8aa3b, v139
	v_exp_f32_e32 v183, v183
	v_exp_f32_e32 v186, v186
	v_lshlrev_b32_e32 v189, 16, v91
	v_lshlrev_b32_e32 v198, 16, v107
	v_mul_f32_e32 v163, v163, v189
	v_mul_f32_e32 v167, v167, v198
	s_add_i32 s71, s71, 1
	v_mul_f32_e32 v189, v183, v163
	v_mul_f32_e32 v198, v183, v167
	v_cvt_pk_bf16_f32 v183, v163, v175
	s_cmp_lt_u32 s71, s70
	v_mul_f32_e32 v188, v186, v175
	v_mul_f32_e32 v186, v186, v187
	v_cvt_pk_bf16_f32 v175, v167, v187
	v_cvt_pk_bf16_f32 v171, v171, v197
	v_cvt_pk_bf16_f32 v163, v179, v196
	v_cvt_pk_bf16_f32 v179, v189, v188
	v_cvt_pk_bf16_f32 v167, v198, v186
	ds_write_b128 v225, v[180:183] offset:36864
	ds_write_b128 v225, v[172:175] offset:37136
	ds_write_b128 v225, v[168:171] offset:54272
	ds_write_b128 v225, v[160:163] offset:54544
	v_add_u32_e32 v160, 0x11800, v225
	s_cselect_b64 s[16:17], -1, 0
	s_cmp_ge_u32 s71, s70
	ds_write_b128 v160, v[176:179]
	ds_write_b128 v160, v[164:167] offset:272
	s_cbranch_scc1 .Lm3h_bar
	v_add_u32_e32 v88, s14, v185
	v_subrev_u32_e32 v120, 31, v88
	v_ashrrev_i32_e32 v121, 31, v120
	v_lshlrev_b64 v[88:89], 14, v[120:121]
	v_lshl_add_u64 v[112:113], v[190:191], 0, v[88:89]
	v_add_co_u32_e32 v96, vcc, 0x4000, v112
	v_lshlrev_b64 v[120:121], 12, v[120:121]
	s_nop 0
	v_addc_co_u32_e32 v97, vcc, 0, v113, vcc
	v_add_co_u32_e32 v114, vcc, 0x1000, v112
	v_lshl_add_u64 v[136:137], v[192:193], 0, v[120:121]
	s_nop 0
	v_addc_co_u32_e32 v115, vcc, 0, v113, vcc
	v_add_co_u32_e32 v116, vcc, 0x5000, v112
	s_ashr_i32 s15, s14, 31
	s_nop 0
	v_addc_co_u32_e32 v117, vcc, 0, v113, vcc
	s_lshl_b64 s[72:73], s[14:15], 12
	v_add_co_u32_e32 v146, vcc, s91, v136
	v_lshl_add_u64 v[144:145], v[192:193], 0, s[72:73]
	s_nop 0
	v_addc_co_u32_e32 v147, vcc, 0, v137, vcc
	v_add_co_u32_e32 v148, vcc, 0x20000, v144
	v_lshl_add_u64 v[156:157], v[144:145], 0, s[34:35]
	v_lshl_add_u64 v[152:153], v[136:137], 0, s[92:93]
	v_addc_co_u32_e32 v149, vcc, 0, v145, vcc
	global_load_dwordx4 v[88:91], v[112:113], off
	global_load_dwordx4 v[92:95], v[112:113], off offset:2048
	global_load_dwordx4 v[104:107], v[96:97], off
	s_nop 0
	global_load_dwordx4 v[96:99], v[96:97], off offset:2048
	s_nop 0
	global_load_dwordx4 v[112:115], v[114:115], off
	s_nop 0
	global_load_dwordx4 v[116:119], v[116:117], off
	s_nop 0
	global_load_dwordx4 v[120:123], v[136:137], off offset:16
	global_load_dwordx4 v[124:127], v[136:137], off
	s_nop 0
	global_load_dwordx4 v[136:139], v[144:145], off offset:16
	global_load_dwordx4 v[140:143], v[144:145], off
	s_nop 0
	global_load_dwordx4 v[144:147], v[146:147], off
	s_nop 0
	global_load_dwordx4 v[148:151], v[148:149], off
	s_nop 0
	global_load_dwordx4 v[152:155], v[152:153], off offset:16
	s_nop 0
	global_load_dwordx4 v[156:159], v[156:157], off offset:16
.Lm3h_bar:
	s_waitcnt lgkmcnt(0)
	s_barrier
.LBB0_1122:
	v_add_u32_e32 v166, s14, v184
	v_add_u32_e32 v208, 0xffffffa1, v166
	v_ashrrev_i32_e32 v209, 31, v208
	v_lshlrev_b64 v[160:161], 14, v[208:209]
	v_add_u32_e32 v204, 0xffffffb1, v166
	v_lshl_add_u64 v[160:161], s[36:37], 0, v[160:161]
	v_ashrrev_i32_e32 v205, 31, v204
	v_lshl_add_u64 v[160:161], v[160:161], 0, s[4:5]
	v_lshlrev_b64 v[162:163], 14, v[204:205]
	v_subrev_u32_e32 v200, 63, v166
	v_lshl_add_u64 v[160:161], v[160:161], 0, s[12:13]
	v_lshl_add_u64 v[162:163], s[36:37], 0, v[162:163]
	v_ashrrev_i32_e32 v201, 31, v200
	v_lshl_add_u64 v[160:161], v[160:161], 0, v[34:35]
	v_lshl_add_u64 v[162:163], v[162:163], 0, s[4:5]
	v_lshlrev_b64 v[164:165], 14, v[200:201]
	v_subrev_u32_e32 v196, 47, v166
	v_add_co_u32_e32 v160, vcc, s91, v160
	v_lshl_add_u64 v[162:163], v[162:163], 0, s[12:13]
	v_lshl_add_u64 v[164:165], s[36:37], 0, v[164:165]
	v_ashrrev_i32_e32 v197, 31, v196
	v_addc_co_u32_e32 v161, vcc, 0, v161, vcc
	v_lshl_add_u64 v[162:163], v[162:163], 0, v[34:35]
	v_lshl_add_u64 v[164:165], v[164:165], 0, s[4:5]
	v_lshlrev_b64 v[166:167], 14, v[196:197]
	v_add_co_u32_e32 v162, vcc, s91, v162
	v_lshl_add_u64 v[164:165], v[164:165], 0, s[12:13]
	v_lshl_add_u64 v[166:167], s[36:37], 0, v[166:167]
	v_addc_co_u32_e32 v163, vcc, 0, v163, vcc
	v_lshl_add_u64 v[164:165], v[164:165], 0, v[34:35]
	v_lshl_add_u64 v[166:167], v[166:167], 0, s[4:5]
	v_add_co_u32_e32 v164, vcc, s91, v164
	v_lshl_add_u64 v[166:167], v[166:167], 0, s[12:13]
	s_nop 0
	v_addc_co_u32_e32 v165, vcc, 0, v165, vcc
	v_lshl_add_u64 v[166:167], v[166:167], 0, v[34:35]
	v_add_co_u32_e32 v166, vcc, 0x1000, v166
	s_nop 1
	v_addc_co_u32_e32 v167, vcc, 0, v167, vcc
	global_load_dwordx2 v[210:211], v[160:161], off offset:2048
	global_load_dwordx2 v[206:207], v[162:163], off offset:2048
	global_load_dwordx2 v[202:203], v[164:165], off offset:2048
	global_load_dwordx2 v[198:199], v[166:167], off offset:2048
	v_mov_b32_e32 v160, 0
	s_andn2_b64 vcc, exec, s[10:11]
	v_mov_b32_e32 v162, 0
	v_mov_b32_e32 v163, 0
	v_mov_b32_e32 v164, 0
	v_mov_b32_e32 v165, 0
	s_cbranch_vccnz .LBB0_1124
	ds_read_b128 v[162:165], v226 offset:54272
	ds_read_b128 v[166:169], v245 offset:36864
	s_waitcnt lgkmcnt(0)
	v_mfma_f32_16x16x32_bf16 v[162:165], v[162:165], v[166:169], 0
	ds_read_b128 v[166:169], v226 offset:54336
	ds_read_b128 v[170:173], v245 offset:36928
	s_waitcnt lgkmcnt(0)
	v_mfma_f32_16x16x32_bf16 v[162:165], v[166:169], v[170:173], v[162:165]
	ds_read_b128 v[166:169], v226 offset:54400
	ds_read_b128 v[170:173], v245 offset:36992
	s_waitcnt lgkmcnt(0)
	v_mfma_f32_16x16x32_bf16 v[162:165], v[166:169], v[170:173], v[162:165]
	ds_read_b128 v[166:169], v226 offset:54464
	ds_read_b128 v[170:173], v245 offset:37056
	s_waitcnt lgkmcnt(0)
	v_mfma_f32_16x16x32_bf16 v[162:165], v[166:169], v[170:173], v[162:165]
